# stack24: QKV epilogue keeps the rope-load vmcnt(0) on the load path only, so groups without rope no longer drain the previous stores (on top of stack22)
# speedup vs baseline: 1.0044x; 1.0044x over previous
;     __device__ __forceinline__ void operator()(const f32x4 (&acc)[2][2][4][2], const Unit& u, int wr, int wc, int fr_in, int fq_in) const {
;     ...
;                     if (isrope) {
; #pragma unroll
;                         for (int m = 0; m < 4; ++m) { const int row = row0 + ai * HALF + m * 16; cs[m] = *(const f32x4*)(CS + (size_t)row * 32 + 4 * fq); sn[m] = *(const f32x4*)(CS + (size_t)row * 32 + 16 + 4 * fq); }
;                     }
.LBB0_283:
	v_add_u32_e32 v136, 0x80, v0
	s_andn2_b64 vcc, exec, s[54:55]
	s_cbranch_vccnz .LBB0_285
	v_mov_b32_e32 v137, v1
	v_readlane_b32 s22, v243, 50
	v_lshlrev_b64 v[66:67], 7, v[136:137]
	v_readlane_b32 s23, v243, 51
	v_lshlrev_b64 v[90:91], 2, v[174:175]
	v_add_u32_e32 v134, 0x90, v0
	v_lshl_add_u64 v[66:67], s[22:23], 0, v[66:67]
	v_lshl_add_u64 v[66:67], v[66:67], 0, v[90:91]
	v_mov_b32_e32 v135, v1
	global_load_dwordx4 v[98:101], v[66:67], off
	global_load_dwordx4 v[94:97], v[66:67], off offset:64
	v_lshlrev_b64 v[66:67], 7, v[134:135]
	v_lshl_add_u64 v[66:67], s[22:23], 0, v[66:67]
	v_lshl_add_u64 v[66:67], v[66:67], 0, v[90:91]
	v_add_u32_e32 v132, 0xa0, v0
	v_mov_b32_e32 v133, v1
	v_add_u32_e32 v130, 0xb0, v0
	v_mov_b32_e32 v131, v1
	global_load_dwordx4 v[86:89], v[66:67], off
	global_load_dwordx4 v[82:85], v[66:67], off offset:64
	v_lshlrev_b64 v[66:67], 7, v[132:133]
	v_lshlrev_b64 v[92:93], 7, v[130:131]
	v_lshl_add_u64 v[66:67], s[22:23], 0, v[66:67]
	v_lshl_add_u64 v[92:93], s[22:23], 0, v[92:93]
	v_lshl_add_u64 v[66:67], v[66:67], 0, v[90:91]
	v_lshl_add_u64 v[102:103], v[92:93], 0, v[90:91]
	global_load_dwordx4 v[70:73], v[66:67], off
	s_nop 0
	global_load_dwordx4 v[66:69], v[66:67], off offset:64
	s_nop 0
	global_load_dwordx4 v[90:93], v[102:103], off
	s_nop 0
	global_load_dwordx4 v[102:105], v[102:103], off offset:64
	s_waitcnt vmcnt(0)
; __device__ __forceinline__ unsigned cvt_pk_bf16(float lo, float hi) { unsigned r; asm volatile("v_cvt_pk_bf16_f32 %0, %1, %2" : "=v"(r) : "v"(lo), "v"(hi)); return r; }
;     __device__ __forceinline__ void operator()(const f32x4 (&acc)[2][2][4][2], const Unit& u, int wr, int wc, int fr_in, int fq_in) const {
;     ...
;                     for (int m = 0; m < 4; ++m) { const int row = row0 + ai * HALF + m * 16;
;                         f32x4 v0 = acc[ai][bj][m][0], v1 = acc[ai][bj][m][1];
;                         if (isrope) { const f32x4 o0 = v0 * cs[m] - v1 * sn[m], o1 = v1 * cs[m] + v0 * sn[m]; v0 = o0; v1 = o1; }
;                         v0 = v0 * QSCALE; v1 = v1 * QSCALE;
;                         bf16_t* p = Q + (size_t)row * QW + X + 4 * fq;
;                         u32x2 a; a.x = cvt_pk_bf16(v0[0], v0[1]); a.y = cvt_pk_bf16(v0[2], v0[3]); *(u32x2*)p = a;
;                         u32x2 b; b.x = cvt_pk_bf16(v1[0], v1[1]); b.y = cvt_pk_bf16(v1[2], v1[3]); *(u32x2*)(p + 16) = b; }
.LBB0_285:
	v_pk_mul_f32 v[138:139], v[124:125], v[96:97]
	v_readlane_b32 s22, v240, 27
	v_pk_fma_f32 v[138:139], v[128:129], v[100:101], v[138:139] neg_lo:[0,0,1] neg_hi:[0,0,1]
	v_pk_mul_f32 v[142:143], v[124:125], v[100:101]
	v_readlane_b32 s23, v240, 28
	v_pk_mul_f32 v[140:141], v[122:123], v[94:95]
	v_pk_mul_f32 v[144:145], v[122:123], v[98:99]
	v_pk_fma_f32 v[142:143], v[128:129], v[96:97], v[142:143]
	v_cndmask_b32_e64 v129, v129, v139, s[40:41]
	v_cndmask_b32_e64 v128, v128, v138, s[40:41]
	v_mov_b64_e32 v[138:139], s[22:23]
	v_pk_fma_f32 v[140:141], v[126:127], v[98:99], v[140:141] neg_lo:[0,0,1] neg_hi:[0,0,1]
	v_pk_fma_f32 v[144:145], v[126:127], v[94:95], v[144:145]
	v_mad_u64_u32 v[136:137], s[22:23], v136, s14, v[138:139]
	v_cndmask_b32_e64 v123, v123, v145, s[40:41]
	v_cndmask_b32_e64 v122, v122, v144, s[40:41]
	v_cndmask_b32_e64 v127, v127, v141, s[40:41]
	v_cndmask_b32_e64 v126, v126, v140, s[40:41]
	v_lshl_add_u64 v[136:137], v[136:137], 0, s[52:53]
	v_cndmask_b32_e64 v125, v125, v143, s[40:41]
	v_cndmask_b32_e64 v124, v124, v142, s[40:41]
	v_pk_mul_f32 v[126:127], v[126:127], s[2:3] op_sel_hi:[1,0]
	v_pk_mul_f32 v[122:123], v[122:123], s[2:3] op_sel_hi:[1,0]
	v_lshl_add_u64 v[136:137], v[136:137], 0, v[154:155]
	v_pk_mul_f32 v[128:129], v[128:129], s[2:3] op_sel_hi:[1,0]
	v_pk_mul_f32 v[124:125], v[124:125], s[2:3] op_sel_hi:[1,0]
	v_cvt_pk_bf16_f32 v126, v126, v127
	v_cvt_pk_bf16_f32 v127, v128, v129
	global_store_dwordx2 v[136:137], v[126:127], off
	v_cvt_pk_bf16_f32 v122, v122, v123
	v_cvt_pk_bf16_f32 v123, v124, v125
	global_store_dwordx2 v[136:137], v[122:123], off offset:32
	v_pk_mul_f32 v[122:123], v[116:117], v[84:85]
	v_pk_mul_f32 v[124:125], v[114:115], v[82:83]
	v_pk_fma_f32 v[122:123], v[120:121], v[88:89], v[122:123] neg_lo:[0,0,1] neg_hi:[0,0,1]
	v_pk_mul_f32 v[126:127], v[116:117], v[88:89]
	v_pk_fma_f32 v[124:125], v[118:119], v[86:87], v[124:125] neg_lo:[0,0,1] neg_hi:[0,0,1]
	v_pk_mul_f32 v[128:129], v[114:115], v[86:87]
	v_pk_fma_f32 v[126:127], v[120:121], v[84:85], v[126:127]
	v_cndmask_b32_e64 v121, v121, v123, s[40:41]
	v_cndmask_b32_e64 v120, v120, v122, s[40:41]
	v_mad_u64_u32 v[122:123], s[22:23], v134, s14, v[138:139]
	v_pk_fma_f32 v[128:129], v[118:119], v[82:83], v[128:129]
	v_cndmask_b32_e64 v118, v118, v124, s[40:41]
	v_mov_b32_e32 v124, v123
	v_cndmask_b32_e64 v119, v119, v125, s[40:41]
	v_mad_u64_u32 v[124:125], s[22:23], v135, s14, v[124:125]
	v_mov_b32_e32 v123, v124
	v_cndmask_b32_e64 v115, v115, v129, s[40:41]
	v_cndmask_b32_e64 v114, v114, v128, s[40:41]
	v_lshl_add_u64 v[122:123], v[122:123], 0, s[52:53]
	v_cndmask_b32_e64 v117, v117, v127, s[40:41]
	v_cndmask_b32_e64 v116, v116, v126, s[40:41]
	v_pk_mul_f32 v[118:119], v[118:119], s[2:3] op_sel_hi:[1,0]
	v_pk_mul_f32 v[114:115], v[114:115], s[2:3] op_sel_hi:[1,0]
	v_lshl_add_u64 v[122:123], v[122:123], 0, v[154:155]
	v_pk_mul_f32 v[120:121], v[120:121], s[2:3] op_sel_hi:[1,0]
	v_pk_mul_f32 v[116:117], v[116:117], s[2:3] op_sel_hi:[1,0]
	v_cvt_pk_bf16_f32 v118, v118, v119
	v_cvt_pk_bf16_f32 v119, v120, v121
	global_store_dwordx2 v[122:123], v[118:119], off
	v_cvt_pk_bf16_f32 v114, v114, v115
	v_cvt_pk_bf16_f32 v115, v116, v117
	global_store_dwordx2 v[122:123], v[114:115], off offset:32
	v_pk_mul_f32 v[114:115], v[108:109], v[68:69]
	v_pk_mul_f32 v[116:117], v[106:107], v[66:67]
	v_pk_fma_f32 v[114:115], v[112:113], v[72:73], v[114:115] neg_lo:[0,0,1] neg_hi:[0,0,1]
	v_pk_mul_f32 v[118:119], v[108:109], v[72:73]
	v_pk_fma_f32 v[116:117], v[110:111], v[70:71], v[116:117] neg_lo:[0,0,1] neg_hi:[0,0,1]
	v_pk_mul_f32 v[120:121], v[106:107], v[70:71]
	v_pk_fma_f32 v[118:119], v[112:113], v[68:69], v[118:119]
	v_cndmask_b32_e64 v113, v113, v115, s[40:41]
	v_cndmask_b32_e64 v112, v112, v114, s[40:41]
	v_mad_u64_u32 v[114:115], s[22:23], v132, s14, v[138:139]
	v_pk_fma_f32 v[120:121], v[110:111], v[66:67], v[120:121]
	v_cndmask_b32_e64 v110, v110, v116, s[40:41]
	v_mov_b32_e32 v116, v115
	v_cndmask_b32_e64 v111, v111, v117, s[40:41]
	v_mad_u64_u32 v[116:117], s[22:23], v133, s14, v[116:117]
	v_mov_b32_e32 v115, v116
	v_cndmask_b32_e64 v107, v107, v121, s[40:41]
	v_cndmask_b32_e64 v106, v106, v120, s[40:41]
	v_lshl_add_u64 v[114:115], v[114:115], 0, s[52:53]
	v_cndmask_b32_e64 v109, v109, v119, s[40:41]
	v_cndmask_b32_e64 v108, v108, v118, s[40:41]
	v_pk_mul_f32 v[110:111], v[110:111], s[2:3] op_sel_hi:[1,0]
	v_pk_mul_f32 v[106:107], v[106:107], s[2:3] op_sel_hi:[1,0]
	v_lshl_add_u64 v[114:115], v[114:115], 0, v[154:155]
	v_pk_mul_f32 v[112:113], v[112:113], s[2:3] op_sel_hi:[1,0]
	v_pk_mul_f32 v[108:109], v[108:109], s[2:3] op_sel_hi:[1,0]
	v_cvt_pk_bf16_f32 v110, v110, v111
	v_cvt_pk_bf16_f32 v111, v112, v113
	global_store_dwordx2 v[114:115], v[110:111], off
	v_cvt_pk_bf16_f32 v106, v106, v107
	v_cvt_pk_bf16_f32 v107, v108, v109
	global_store_dwordx2 v[114:115], v[106:107], off offset:32
	v_pk_mul_f32 v[106:107], v[76:77], v[104:105]
	v_pk_mul_f32 v[108:109], v[74:75], v[102:103]
	v_pk_fma_f32 v[106:107], v[80:81], v[92:93], v[106:107] neg_lo:[0,0,1] neg_hi:[0,0,1]
	v_pk_mul_f32 v[110:111], v[76:77], v[92:93]
	v_pk_fma_f32 v[108:109], v[78:79], v[90:91], v[108:109] neg_lo:[0,0,1] neg_hi:[0,0,1]
	v_pk_mul_f32 v[112:113], v[74:75], v[90:91]
	v_pk_fma_f32 v[110:111], v[80:81], v[104:105], v[110:111]
	v_cndmask_b32_e64 v81, v81, v107, s[40:41]
	v_cndmask_b32_e64 v80, v80, v106, s[40:41]
	v_mad_u64_u32 v[106:107], s[22:23], v130, s14, v[138:139]
	v_pk_fma_f32 v[112:113], v[78:79], v[102:103], v[112:113]
	v_cndmask_b32_e64 v78, v78, v108, s[40:41]
	v_mov_b32_e32 v108, v107
	v_cndmask_b32_e64 v79, v79, v109, s[40:41]
	v_mad_u64_u32 v[108:109], s[22:23], v131, s14, v[108:109]
	v_mov_b32_e32 v107, v108
	v_cndmask_b32_e64 v75, v75, v113, s[40:41]
	v_cndmask_b32_e64 v74, v74, v112, s[40:41]
	v_lshl_add_u64 v[106:107], v[106:107], 0, s[52:53]
	v_cndmask_b32_e64 v77, v77, v111, s[40:41]
	v_cndmask_b32_e64 v76, v76, v110, s[40:41]
	v_pk_mul_f32 v[78:79], v[78:79], s[2:3] op_sel_hi:[1,0]
	v_pk_mul_f32 v[74:75], v[74:75], s[2:3] op_sel_hi:[1,0]
	v_lshl_add_u64 v[106:107], v[106:107], 0, v[154:155]
	v_pk_mul_f32 v[80:81], v[80:81], s[2:3] op_sel_hi:[1,0]
	v_pk_mul_f32 v[76:77], v[76:77], s[2:3] op_sel_hi:[1,0]
	v_cvt_pk_bf16_f32 v78, v78, v79
	v_cvt_pk_bf16_f32 v79, v80, v81
	global_store_dwordx2 v[106:107], v[78:79], off
	v_cvt_pk_bf16_f32 v74, v74, v75
	v_cvt_pk_bf16_f32 v75, v76, v77
	global_store_dwordx2 v[106:107], v[74:75], off offset:32
	s_or_b32 s16, s50, 0x80
	s_cmpk_lt_i32 s16, 0x300
	s_mov_b64 s[40:41], -1
	s_cbranch_scc0 .LBB0_297

;     __device__ __forceinline__ void operator()(const f32x4 (&acc)[2][2][4][2], const Unit& u, int wr, int wc, int fr_in, int fq_in) const {
;     ...
;                     if (isrope) {
; #pragma unroll
;                         for (int m = 0; m < 4; ++m) { const int row = row0 + ai * HALF + m * 16; cs[m] = *(const f32x4*)(CS + (size_t)row * 32 + 4 * fq); sn[m] = *(const f32x4*)(CS + (size_t)row * 32 + 16 + 4 * fq); }
;                     }
.LBB0_289:
	s_andn2_b64 vcc, exec, s[54:55]
	v_lshlrev_b64 v[74:75], 2, v[174:175]
	s_cbranch_vccnz .LBB0_291
	v_readlane_b32 s4, v243, 50
	v_lshlrev_b64 v[66:67], 7, v[0:1]
	v_readlane_b32 s5, v243, 51
	v_mov_b32_e32 v81, v1
	v_mov_b32_e32 v79, v1
	v_lshl_add_u64 v[66:67], s[4:5], 0, v[66:67]
	v_lshl_add_u64 v[66:67], v[66:67], 0, v[74:75]
	global_load_dwordx4 v[98:101], v[66:67], off
	global_load_dwordx4 v[94:97], v[66:67], off offset:64
	v_lshlrev_b64 v[66:67], 7, v[80:81]
	v_lshl_add_u64 v[66:67], s[4:5], 0, v[66:67]
	v_lshl_add_u64 v[66:67], v[66:67], 0, v[74:75]
	v_mov_b32_e32 v77, v1
	global_load_dwordx4 v[86:89], v[66:67], off
	global_load_dwordx4 v[82:85], v[66:67], off offset:64
	v_lshlrev_b64 v[66:67], 7, v[78:79]
	v_lshlrev_b64 v[90:91], 7, v[76:77]
	v_lshl_add_u64 v[66:67], s[4:5], 0, v[66:67]
	v_lshl_add_u64 v[90:91], s[4:5], 0, v[90:91]
	v_lshl_add_u64 v[66:67], v[66:67], 0, v[74:75]
	v_lshl_add_u64 v[102:103], v[90:91], 0, v[74:75]
	global_load_dwordx4 v[70:73], v[66:67], off
	s_nop 0
	global_load_dwordx4 v[66:69], v[66:67], off offset:64
	s_nop 0
	global_load_dwordx4 v[90:93], v[102:103], off
	s_nop 0
	global_load_dwordx4 v[102:105], v[102:103], off offset:64
	s_waitcnt vmcnt(0)
; __device__ __forceinline__ unsigned cvt_pk_bf16(float lo, float hi) { unsigned r; asm volatile("v_cvt_pk_bf16_f32 %0, %1, %2" : "=v"(r) : "v"(lo), "v"(hi)); return r; }
;     __device__ __forceinline__ void operator()(const f32x4 (&acc)[2][2][4][2], const Unit& u, int wr, int wc, int fr_in, int fq_in) const {
;     ...
;                     for (int m = 0; m < 4; ++m) { const int row = row0 + ai * HALF + m * 16;
;                         f32x4 v0 = acc[ai][bj][m][0], v1 = acc[ai][bj][m][1];
;                         if (isrope) { const f32x4 o0 = v0 * cs[m] - v1 * sn[m], o1 = v1 * cs[m] + v0 * sn[m]; v0 = o0; v1 = o1; }
;                         v0 = v0 * QSCALE; v1 = v1 * QSCALE;
;                         bf16_t* p = Q + (size_t)row * QW + X + 4 * fq;
;                         u32x2 a; a.x = cvt_pk_bf16(v0[0], v0[1]); a.y = cvt_pk_bf16(v0[2], v0[3]); *(u32x2*)p = a;
;                         u32x2 b; b.x = cvt_pk_bf16(v1[0], v1[1]); b.y = cvt_pk_bf16(v1[2], v1[3]); *(u32x2*)(p + 16) = b; }
.LBB0_291:
	v_pk_mul_f32 v[108:109], v[58:59], v[94:95]
	v_pk_mul_f32 v[112:113], v[58:59], v[98:99]
	v_readlane_b32 s4, v240, 27
	v_pk_mul_f32 v[106:107], v[60:61], v[96:97]
	v_pk_fma_f32 v[108:109], v[62:63], v[98:99], v[108:109] neg_lo:[0,0,1] neg_hi:[0,0,1]
	v_pk_fma_f32 v[112:113], v[62:63], v[94:95], v[112:113]
	v_readlane_b32 s5, v240, 28
	v_pk_fma_f32 v[106:107], v[64:65], v[100:101], v[106:107] neg_lo:[0,0,1] neg_hi:[0,0,1]
	v_pk_mul_f32 v[110:111], v[60:61], v[100:101]
	v_cndmask_b32_e64 v59, v59, v113, s[40:41]
	v_cndmask_b32_e64 v58, v58, v112, s[40:41]
	v_cndmask_b32_e64 v63, v63, v109, s[40:41]
	v_cndmask_b32_e64 v62, v62, v108, s[40:41]
	s_mov_b32 s2, 0x3e16c740
	v_mov_b64_e32 v[108:109], s[4:5]
	s_ashr_i32 s51, s50, 31
	v_pk_fma_f32 v[110:111], v[64:65], v[96:97], v[110:111]
	v_cndmask_b32_e64 v65, v65, v107, s[40:41]
	v_cndmask_b32_e64 v64, v64, v106, s[40:41]
	v_pk_mul_f32 v[106:107], v[58:59], s[2:3] op_sel_hi:[1,0]
	v_mad_u64_u32 v[58:59], s[4:5], v0, s14, v[108:109]
	s_lshl_b64 s[50:51], s[50:51], 1
	v_cndmask_b32_e64 v61, v61, v111, s[40:41]
	v_cndmask_b32_e64 v60, v60, v110, s[40:41]
	v_pk_mul_f32 v[62:63], v[62:63], s[2:3] op_sel_hi:[1,0]
	v_lshl_add_u64 v[110:111], v[58:59], 0, s[50:51]
	v_lshlrev_b64 v[58:59], 1, v[174:175]
	v_pk_mul_f32 v[64:65], v[64:65], s[2:3] op_sel_hi:[1,0]
	v_pk_mul_f32 v[60:61], v[60:61], s[2:3] op_sel_hi:[1,0]
	v_lshl_add_u64 v[110:111], v[110:111], 0, v[58:59]
	v_cvt_pk_bf16_f32 v62, v62, v63
	v_cvt_pk_bf16_f32 v63, v64, v65
	global_store_dwordx2 v[110:111], v[62:63], off offset:256
	v_cvt_pk_bf16_f32 v62, v106, v107
	v_cvt_pk_bf16_f32 v63, v60, v61
	v_pk_mul_f32 v[60:61], v[52:53], v[84:85]
	global_store_dwordx2 v[110:111], v[62:63], off offset:288
	v_pk_mul_f32 v[62:63], v[50:51], v[82:83]
	v_pk_fma_f32 v[60:61], v[56:57], v[88:89], v[60:61] neg_lo:[0,0,1] neg_hi:[0,0,1]
	v_pk_mul_f32 v[64:65], v[52:53], v[88:89]
	v_pk_fma_f32 v[62:63], v[54:55], v[86:87], v[62:63] neg_lo:[0,0,1] neg_hi:[0,0,1]
	v_pk_mul_f32 v[106:107], v[50:51], v[86:87]
	v_pk_fma_f32 v[64:65], v[56:57], v[84:85], v[64:65]
	v_cndmask_b32_e64 v57, v57, v61, s[40:41]
	v_cndmask_b32_e64 v56, v56, v60, s[40:41]
	v_mad_u64_u32 v[60:61], s[4:5], v80, s14, v[108:109]
	v_pk_fma_f32 v[106:107], v[54:55], v[82:83], v[106:107]
	v_cndmask_b32_e64 v54, v54, v62, s[40:41]
	v_mov_b32_e32 v62, v61
	v_cndmask_b32_e64 v55, v55, v63, s[40:41]
	v_mad_u64_u32 v[62:63], s[4:5], v81, s14, v[62:63]
	v_mov_b32_e32 v61, v62
	v_cndmask_b32_e64 v51, v51, v107, s[40:41]
	v_cndmask_b32_e64 v50, v50, v106, s[40:41]
	v_lshl_add_u64 v[60:61], v[60:61], 0, s[50:51]
	v_cndmask_b32_e64 v53, v53, v65, s[40:41]
	v_cndmask_b32_e64 v52, v52, v64, s[40:41]
	v_pk_mul_f32 v[54:55], v[54:55], s[2:3] op_sel_hi:[1,0]
	v_pk_mul_f32 v[50:51], v[50:51], s[2:3] op_sel_hi:[1,0]
	v_lshl_add_u64 v[60:61], v[60:61], 0, v[58:59]
	v_pk_mul_f32 v[56:57], v[56:57], s[2:3] op_sel_hi:[1,0]
	v_pk_mul_f32 v[52:53], v[52:53], s[2:3] op_sel_hi:[1,0]
	v_cvt_pk_bf16_f32 v54, v54, v55
	v_cvt_pk_bf16_f32 v55, v56, v57
	global_store_dwordx2 v[60:61], v[54:55], off offset:256
	v_cvt_pk_bf16_f32 v50, v50, v51
	v_cvt_pk_bf16_f32 v51, v52, v53
	global_store_dwordx2 v[60:61], v[50:51], off offset:288
	v_pk_mul_f32 v[50:51], v[44:45], v[68:69]
	v_pk_mul_f32 v[52:53], v[42:43], v[66:67]
	v_pk_fma_f32 v[50:51], v[48:49], v[72:73], v[50:51] neg_lo:[0,0,1] neg_hi:[0,0,1]
	v_pk_mul_f32 v[54:55], v[44:45], v[72:73]
	v_pk_fma_f32 v[52:53], v[46:47], v[70:71], v[52:53] neg_lo:[0,0,1] neg_hi:[0,0,1]
	v_pk_mul_f32 v[56:57], v[42:43], v[70:71]
	v_pk_fma_f32 v[54:55], v[48:49], v[68:69], v[54:55]
	v_cndmask_b32_e64 v49, v49, v51, s[40:41]
	v_cndmask_b32_e64 v48, v48, v50, s[40:41]
	v_mad_u64_u32 v[50:51], s[4:5], v78, s14, v[108:109]
	v_pk_fma_f32 v[56:57], v[46:47], v[66:67], v[56:57]
	v_cndmask_b32_e64 v46, v46, v52, s[40:41]
	v_mov_b32_e32 v52, v51
	v_cndmask_b32_e64 v47, v47, v53, s[40:41]
	v_mad_u64_u32 v[52:53], s[4:5], v79, s14, v[52:53]
	v_mov_b32_e32 v51, v52
	v_cndmask_b32_e64 v43, v43, v57, s[40:41]
	v_cndmask_b32_e64 v42, v42, v56, s[40:41]
	v_lshl_add_u64 v[50:51], v[50:51], 0, s[50:51]
	v_cndmask_b32_e64 v45, v45, v55, s[40:41]
	v_cndmask_b32_e64 v44, v44, v54, s[40:41]
	v_pk_mul_f32 v[46:47], v[46:47], s[2:3] op_sel_hi:[1,0]
	v_pk_mul_f32 v[42:43], v[42:43], s[2:3] op_sel_hi:[1,0]
	v_lshl_add_u64 v[50:51], v[50:51], 0, v[58:59]
	v_pk_mul_f32 v[48:49], v[48:49], s[2:3] op_sel_hi:[1,0]
	v_pk_mul_f32 v[44:45], v[44:45], s[2:3] op_sel_hi:[1,0]
	v_cvt_pk_bf16_f32 v46, v46, v47
	v_cvt_pk_bf16_f32 v47, v48, v49
	global_store_dwordx2 v[50:51], v[46:47], off offset:256
	v_cvt_pk_bf16_f32 v42, v42, v43
	v_cvt_pk_bf16_f32 v43, v44, v45
	global_store_dwordx2 v[50:51], v[42:43], off offset:288
	v_pk_mul_f32 v[42:43], v[36:37], v[104:105]
	v_pk_mul_f32 v[44:45], v[34:35], v[102:103]
	v_pk_fma_f32 v[42:43], v[40:41], v[92:93], v[42:43] neg_lo:[0,0,1] neg_hi:[0,0,1]
	v_pk_mul_f32 v[46:47], v[36:37], v[92:93]
	v_pk_fma_f32 v[44:45], v[38:39], v[90:91], v[44:45] neg_lo:[0,0,1] neg_hi:[0,0,1]
	v_pk_mul_f32 v[48:49], v[34:35], v[90:91]
	v_pk_fma_f32 v[46:47], v[40:41], v[104:105], v[46:47]
	v_cndmask_b32_e64 v41, v41, v43, s[40:41]
	v_cndmask_b32_e64 v40, v40, v42, s[40:41]
	v_mad_u64_u32 v[42:43], s[4:5], v76, s14, v[108:109]
	v_pk_fma_f32 v[48:49], v[38:39], v[102:103], v[48:49]
	v_cndmask_b32_e64 v38, v38, v44, s[40:41]
	v_mov_b32_e32 v44, v43
	v_cndmask_b32_e64 v39, v39, v45, s[40:41]
	v_mad_u64_u32 v[44:45], s[4:5], v77, s14, v[44:45]
	v_mov_b32_e32 v43, v44
	v_cndmask_b32_e64 v35, v35, v49, s[40:41]
	v_cndmask_b32_e64 v34, v34, v48, s[40:41]
	v_lshl_add_u64 v[42:43], v[42:43], 0, s[50:51]
	v_cndmask_b32_e64 v37, v37, v47, s[40:41]
	v_cndmask_b32_e64 v36, v36, v46, s[40:41]
	v_pk_mul_f32 v[38:39], v[38:39], s[2:3] op_sel_hi:[1,0]
	v_pk_mul_f32 v[34:35], v[34:35], s[2:3] op_sel_hi:[1,0]
	v_lshl_add_u64 v[42:43], v[42:43], 0, v[58:59]
	v_pk_mul_f32 v[40:41], v[40:41], s[2:3] op_sel_hi:[1,0]
	v_pk_mul_f32 v[36:37], v[36:37], s[2:3] op_sel_hi:[1,0]
	v_cvt_pk_bf16_f32 v38, v38, v39
	v_cvt_pk_bf16_f32 v39, v40, v41
	global_store_dwordx2 v[42:43], v[38:39], off offset:256
	v_cvt_pk_bf16_f32 v34, v34, v35
	v_cvt_pk_bf16_f32 v35, v36, v37
	global_store_dwordx2 v[42:43], v[34:35], off offset:288
	s_mov_b64 s[54:55], -1
	s_andn2_b64 vcc, exec, s[52:53]
	v_add_u32_e32 v38, 0x90, v0
	v_add_u32_e32 v36, 0xa0, v0
	v_add_u32_e32 v34, 0xb0, v0
	s_cbranch_vccnz .LBB0_293
	v_mov_b32_e32 v39, v1
	v_mov_b32_e32 v37, v1
	v_mov_b32_e32 v35, v1
	s_mov_b64 s[54:55], 0
